# v68 plus prompt-attention selection mask without the two s_nop 0 per element
# speedup vs baseline: 1.0121x; 1.0057x over previous
.Lml_done:
	s_waitcnt vmcnt(3) lgkmcnt(0)
	s_barrier
	ds_read_b128 v[4:7], v235
	ds_read_b128 v[20:23], v235 offset:512
	ds_read_b128 v[36:39], v235 offset:2048
	v_add3_u32 v209, s6, v249, v243
	s_lshl_b32 s22, s53, 2
	s_add_i32 s53, s22, 0
	s_mov_b32 s4, 0
	s_movk_i32 s60, 0x2000
	s_movk_i32 s62, 0x4000
	s_lshr_b32 s59, s59, 6
	s_mov_b32 s22, 1
	v_lshl_add_u32 v207, v100, 2, s53
	s_waitcnt vmcnt(3) lgkmcnt(2)
	v_mfma_f32_32x32x16_bf16 v[4:19], v[4:7], v[130:133], 0
	s_waitcnt vmcnt(2) lgkmcnt(0)
	v_mfma_f32_32x32x16_bf16 v[4:19], v[36:39], v[126:129], v[4:19]
	ds_read_b128 v[36:39], v235 offset:2560
	v_mfma_f32_32x32x16_bf16 v[20:35], v[20:23], v[130:133], 0
	s_waitcnt lgkmcnt(0)
	v_mfma_f32_32x32x16_bf16 v[20:35], v[36:39], v[126:129], v[20:35]
	ds_read_b128 v[36:39], v235 offset:4096
	ds_read_b128 v[40:43], v235 offset:4608
	s_waitcnt vmcnt(1) lgkmcnt(1)
	v_mfma_f32_32x32x16_bf16 v[4:19], v[36:39], v[122:125], v[4:19]
	ds_read_b128 v[36:39], v235 offset:6656
	ds_read_b128 v[44:47], v235 offset:6144
	s_waitcnt lgkmcnt(2)
	v_mfma_f32_32x32x16_bf16 v[20:35], v[40:43], v[122:125], v[20:35]
	s_waitcnt vmcnt(0) lgkmcnt(0)
	v_mfma_f32_32x32x16_bf16 v[4:19], v[44:47], v[114:117], v[4:19]
	v_mfma_f32_32x32x16_bf16 v[20:35], v[36:39], v[114:117], v[20:35]
	s_nop 15
	s_nop 7
	ds_read_b32 v2, v209
	s_waitcnt lgkmcnt(0)
	v_bfe_i32 v36, v2, 0, 1
	v_bfi_b32 v4, v36, s49, v4
	s_waitcnt vmcnt(0) lgkmcnt(0)
	s_barrier
	v_bfe_i32 v36, v2, 1, 1
	v_bfi_b32 v5, v36, s49, v5
	v_bfe_i32 v36, v2, 2, 1
	v_bfi_b32 v6, v36, s49, v6
	v_bfe_i32 v36, v2, 3, 1
	v_bfi_b32 v7, v36, s49, v7
	v_bfe_i32 v36, v2, 4, 1
	v_bfi_b32 v8, v36, s49, v8
	v_bfe_i32 v36, v2, 5, 1
	v_bfi_b32 v9, v36, s49, v9
	v_bfe_i32 v36, v2, 6, 1
	v_bfi_b32 v10, v36, s49, v10
	v_bfe_i32 v36, v2, 7, 1
	v_bfi_b32 v11, v36, s49, v11
	v_bfe_i32 v36, v2, 8, 1
	v_bfi_b32 v12, v36, s49, v12
	v_bfe_i32 v36, v2, 9, 1
	v_bfi_b32 v13, v36, s49, v13
	v_bfe_i32 v36, v2, 10, 1
	v_bfi_b32 v14, v36, s49, v14
	v_bfe_i32 v36, v2, 11, 1
	v_bfi_b32 v15, v36, s49, v15
	v_bfe_i32 v36, v2, 12, 1
	v_bfi_b32 v16, v36, s49, v16
	v_bfe_i32 v36, v2, 13, 1
	v_bfi_b32 v17, v36, s49, v17
	v_bfe_i32 v36, v2, 14, 1
	v_bfi_b32 v18, v36, s49, v18
	v_bfe_i32 v36, v2, 15, 1
	v_bfi_b32 v19, v36, s49, v19
	v_bfe_i32 v36, v2, 16, 1
	v_bfi_b32 v20, v36, s49, v20
	v_bfe_i32 v36, v2, 17, 1
	v_bfi_b32 v21, v36, s49, v21
	v_bfe_i32 v36, v2, 18, 1
	v_bfi_b32 v22, v36, s49, v22
	v_bfe_i32 v36, v2, 19, 1
	v_bfi_b32 v23, v36, s49, v23
	v_bfe_i32 v36, v2, 20, 1
	v_bfi_b32 v24, v36, s49, v24
	v_bfe_i32 v36, v2, 21, 1
	v_bfi_b32 v25, v36, s49, v25
	v_bfe_i32 v36, v2, 22, 1
	v_bfi_b32 v26, v36, s49, v26
	v_bfe_i32 v36, v2, 23, 1
	v_bfi_b32 v27, v36, s49, v27
	v_bfe_i32 v36, v2, 24, 1
	v_bfi_b32 v28, v36, s49, v28
	v_bfe_i32 v36, v2, 25, 1
	v_bfi_b32 v29, v36, s49, v29
	v_bfe_i32 v36, v2, 26, 1
	v_bfi_b32 v30, v36, s49, v30
	v_bfe_i32 v36, v2, 27, 1
	v_bfi_b32 v31, v36, s49, v31
	v_bfe_i32 v36, v2, 28, 1
	v_bfi_b32 v32, v36, s49, v32
	v_bfe_i32 v36, v2, 29, 1
	v_bfi_b32 v33, v36, s49, v33
	v_bfe_i32 v36, v2, 30, 1
	v_bfi_b32 v34, v36, s49, v34
	v_bfe_i32 v36, v2, 31, 1
	v_bfi_b32 v35, v36, s49, v35
	s_nop 0
	v_max3_f32 v2, v4, v5, v20
	s_nop 0
	v_max3_f32 v36, v6, v7, v21
	v_max3_f32 v2, v2, v22, v23
	s_nop 0
	v_max3_f32 v36, v36, v10, v11
	v_max3_f32 v2, v2, v8, v9
	s_nop 0
	v_max3_f32 v36, v36, v26, v27
	v_max3_f32 v2, v2, v24, v25
	s_nop 0
	v_max3_f32 v36, v36, v14, v15
	v_max3_f32 v2, v2, v12, v13
	s_nop 0
	v_max3_f32 v36, v36, v30, v31
	v_max3_f32 v2, v2, v28, v29
	s_nop 0
	v_max3_f32 v36, v36, v18, v19
	v_max3_f32 v2, v2, v16, v17
	s_nop 0
	v_max3_f32 v36, v36, v34, v35
	v_max3_f32 v2, v2, v32, v33
	s_nop 0
	v_max_f32_e32 v2, v2, v36
	s_nop 0
	v_mov_b32_e32 v36, v2
	s_nop 1
	v_permlane32_swap_b32_e32 v2, v36
	v_max_f32_e32 v2, v2, v36
	s_nop 0
	v_cmp_ngt_f32_e32 vcc, s50, v2
	s_nop 1
	v_cndmask_b32_e32 v2, 0, v2, vcc
	v_sub_f32_e32 v4, v4, v2
	v_sub_f32_e32 v5, v5, v2
	v_add_f32_e32 v211, v3, v2
	v_sub_f32_e32 v20, v20, v2
	v_sub_f32_e32 v21, v21, v2
	v_sub_f32_e32 v6, v6, v2
	s_nop 0
	v_exp_f32_e32 v52, v4
	v_exp_f32_e32 v53, v5
	v_lshl_add_u64 v[4:5], v[220:221], 0, s[30:31]
	s_mov_b32 s63, m0
	s_mov_b32 m0, s57
	s_nop 0
	global_load_lds_dwordx4 v[4:5], off
	s_mov_b32 m0, s63
	v_lshl_add_u64 v[4:5], v[222:223], 0, s[26:27]
	s_add_i32 s63, s57, 0x8000
	s_mov_b32 s64, m0
	s_mov_b32 m0, s63
	s_nop 0
	global_load_lds_dwordx4 v[4:5], off
	s_mov_b32 m0, s64
	ds_read_b128 v[162:165], v235 offset:8192
	ds_read_b128 v[158:161], v235 offset:8704
	ds_read_b128 v[154:157], v235 offset:10240
	ds_read_b128 v[150:153], v235 offset:10752
	ds_read_b128 v[146:149], v235 offset:12288
	ds_read_b128 v[142:145], v235 offset:12800
	ds_read_b128 v[138:141], v235 offset:14336
	ds_read_b128 v[134:137], v235 offset:14848
	v_sub_f32_e32 v22, v22, v2
	v_sub_f32_e32 v7, v7, v2
	v_sub_f32_e32 v23, v23, v2
	v_sub_f32_e32 v8, v8, v2
	v_sub_f32_e32 v24, v24, v2
	v_sub_f32_e32 v9, v9, v2
	v_sub_f32_e32 v25, v25, v2
	v_sub_f32_e32 v10, v10, v2
	v_sub_f32_e32 v26, v26, v2
	v_sub_f32_e32 v11, v11, v2
	v_sub_f32_e32 v27, v27, v2
	v_sub_f32_e32 v12, v12, v2
	v_sub_f32_e32 v28, v28, v2
	v_sub_f32_e32 v13, v13, v2
	v_sub_f32_e32 v29, v29, v2
	v_sub_f32_e32 v14, v14, v2
	v_sub_f32_e32 v30, v30, v2
	v_sub_f32_e32 v15, v15, v2
	v_sub_f32_e32 v31, v31, v2
	v_sub_f32_e32 v16, v16, v2
	v_sub_f32_e32 v32, v32, v2
	v_sub_f32_e32 v17, v17, v2
	v_sub_f32_e32 v33, v33, v2
	v_sub_f32_e32 v18, v18, v2
	v_sub_f32_e32 v34, v34, v2
	v_sub_f32_e32 v19, v19, v2
	v_sub_f32_e32 v2, v35, v2
	v_exp_f32_e32 v54, v6
	v_exp_f32_e32 v55, v7
	v_exp_f32_e32 v56, v8
	v_exp_f32_e32 v57, v9
	v_exp_f32_e32 v58, v10
	v_exp_f32_e32 v59, v11
	v_exp_f32_e32 v60, v12
	v_exp_f32_e32 v61, v13
	v_exp_f32_e32 v62, v14
	v_exp_f32_e32 v63, v15
	v_exp_f32_e32 v64, v16
	v_exp_f32_e32 v65, v17
	v_exp_f32_e32 v66, v18
	v_exp_f32_e32 v67, v19
	v_exp_f32_e32 v36, v20
	v_exp_f32_e32 v37, v21
	v_exp_f32_e32 v38, v22
	v_exp_f32_e32 v39, v23
	v_exp_f32_e32 v40, v24
	v_exp_f32_e32 v41, v25
	v_exp_f32_e32 v42, v26
	v_exp_f32_e32 v43, v27
	v_exp_f32_e32 v44, v28
	v_exp_f32_e32 v45, v29
	v_exp_f32_e32 v46, v30
	v_exp_f32_e32 v47, v31
	v_exp_f32_e32 v48, v32
	v_exp_f32_e32 v49, v33
	v_exp_f32_e32 v50, v34
	v_exp_f32_e32 v51, v2
	s_waitcnt vmcnt(2) lgkmcnt(0)
	s_barrier
	s_andn2_b64 vcc, exec, s[42:43]
	s_cbranch_vccnz .LBB0_1962
	v_mov_b32_e32 v16, v3
	v_mov_b32_e32 v17, v3
	v_mov_b32_e32 v2, v3
	v_mov_b32_e32 v4, v3
	v_mov_b32_e32 v5, v3
	v_mov_b32_e32 v6, v3
	v_mov_b32_e32 v7, v3
	v_mov_b32_e32 v8, v3
	v_mov_b32_e32 v9, v3
	v_mov_b32_e32 v10, v3
	v_mov_b32_e32 v11, v3
	v_mov_b32_e32 v12, v3
	v_mov_b32_e32 v13, v3
	v_mov_b32_e32 v14, v3
	v_mov_b32_e32 v15, v3
	v_mov_b64_e32 v[34:35], v[16:17]
	v_mov_b64_e32 v[32:33], v[14:15]
	v_mov_b64_e32 v[30:31], v[12:13]
	v_mov_b64_e32 v[28:29], v[10:11]
	v_mov_b64_e32 v[26:27], v[8:9]
	v_mov_b64_e32 v[24:25], v[6:7]
	v_mov_b64_e32 v[22:23], v[4:5]
	v_mov_b64_e32 v[20:21], v[2:3]
	v_mov_b64_e32 v[18:19], v[16:17]
	v_add_u32_e32 v182, s61, v244
	s_mov_b32 s8, 0
	s_movk_i32 s4, 0x4000
	s_movk_i32 s12, 0x2000
	v_mov_b32_e32 v213, 0
	s_mov_b32 s5, 6
	s_mov_b64 s[6:7], 0
	v_mov_b64_e32 v[16:17], v[14:15]
	v_mov_b64_e32 v[14:15], v[12:13]
	v_mov_b64_e32 v[12:13], v[10:11]
	v_mov_b64_e32 v[10:11], v[8:9]
	v_mov_b64_e32 v[8:9], v[6:7]
	v_mov_b64_e32 v[6:7], v[4:5]
	v_mov_b64_e32 v[4:5], v[2:3]
